# v50 plus conversion schedule shifted toward the prologue (P=16640, G=8400) and class-B share 1728
# speedup vs baseline: 1.0064x; 1.0009x over previous
; #define KP() ({ KArgs kp_ = kp0; asm volatile("" : "+s"(kp_)); kp_; })
; #define G_ ({ int g__ = (int)gridDim.x; asm volatile("" : "+s"(g__)); g__; })
; #define c_ ({ int c__ = (int)blockIdx.x; asm volatile("" : "+s"(c__)); c__; })
; __global__ void __launch_bounds__(512, 2) mega(MegaArgs a) {
;     ...
;             { const int rem = ((T_SEQ / 256) * (NGU / 256)) % G_, q = 3 * l + (half ? 2 : 0), hi = cvt_slot_hi(q) < CVT_TOTAL ? cvt_slot_hi(q) : CVT_TOTAL;
;               if (!(hf & 2) && rem && c_ >= rem && cvt_slot_lo(q) < hi) { KArgs kq = KP(); convert_range(kq, lds, cvt_slot_lo(q), hi, c_ - rem, G_ - rem); } }
.LBB0_308:
	s_mov_b32 s0, s21
	s_abs_i32 s0, s0
	v_cvt_f32_u32_e32 v1, s0
	s_sub_i32 s1, 0, s0
	v_rcp_iflag_f32_e32 v1, v1
	s_nop 0
	v_mul_f32_e32 v1, 0x4f7ffffe, v1
	v_cvt_u32_f32_e32 v1, v1
	s_nop 0
	v_readfirstlane_b32 s2, v1
	s_mul_i32 s1, s1, s2
	s_mul_hi_u32 s1, s2, s1
	s_add_i32 s2, s2, s1
	s_mul_hi_u32 s1, s2, 0x560
	s_mul_i32 s1, s1, s0
	s_sub_i32 s1, 0x560, s1
	s_sub_i32 s2, s1, s0
	s_cmp_ge_u32 s1, s0
	s_cselect_b32 s1, s2, s1
	s_sub_i32 s2, s1, s0
	s_cmp_ge_u32 s1, s0
	v_readlane_b32 s0, v251, 24
	s_cselect_b32 s44, s2, s1
	s_movk_i32 s44, 0xa0
	s_bitcmp1_b32 s0, 1
	s_cselect_b64 s[0:1], -1, 0
	s_cmp_eq_u32 s44, 0
	s_cselect_b64 s[4:5], -1, 0
	s_or_b64 s[0:1], s[0:1], s[4:5]
	s_and_b64 vcc, exec, s[0:1]
	s_cbranch_vccnz .LBB0_496
	v_readlane_b32 s0, v251, 22
	v_readlane_b32 s1, v251, 23
	s_mul_i32 s0, s0, 3
	s_lshl_b32 s1, s52, 1
	s_add_i32 s1, s1, s0
	s_mul_hi_i32 s0, s1, 0x55555556
	s_lshr_b32 s2, s0, 31
	s_add_i32 s0, s0, s2
	s_mul_i32 s2, s0, 3
	s_sub_i32 s1, s1, s2
	s_cmp_eq_u32 s1, 1
	s_movk_i32 s2, 0x20d0
	s_movk_i32 s4, 0x1ce8
	s_cselect_b32 s2, s2, 0x3db8
	s_cselect_b32 s4, s4, 0x20d0
	s_cmp_lg_u32 s1, 0
	s_mulk_i32 s0, 0x5e88
	s_cselect_b32 s1, s2, 0
	s_add_i32 s2, s0, s1
	s_addk_i32 s2, 0x4100
	s_add_i32 s0, s2, s4
	s_min_i32 s26, s0, 0x1a500
	s_mov_b32 s0, s67
	s_cmp_ge_i32 s0, s44
	s_cselect_b64 s[0:1], -1, 0
	s_cmp_lt_i32 s2, s26
	s_cselect_b64 s[4:5], -1, 0
	s_and_b64 s[0:1], s[0:1], s[4:5]
	s_andn2_b64 vcc, exec, s[0:1]
	s_cbranch_vccnz .LBB0_496
	s_mov_b64 s[0:1], s[70:71]
	s_mov_b32 s4, s67
	s_sub_i32 s4, s4, s44
	s_mov_b32 s45, s21
	s_cmp_lt_u32 s4, 32
	s_cbranch_scc1 .Lrb1_B
	s_sub_i32 s4, s4, 32
	s_movk_i32 s44, 0xc0
	s_addk_i32 s2, 0x6c0
	s_branch .Lrb1_done
.Lrb1_B:
	s_movk_i32 s45, 0xc0
	s_add_i32 s27, s2, 0x6c0
	s_min_i32 s26, s26, s27
